# attention item: compressed-branch gate scalar loaded at item start instead of right before a block sync
# baseline (speedup 1.0000x reference)
.LBB0_1077:
	s_or_b64 exec, exec, s[4:5]
	s_add_u32 s80, s76, s2
	s_addc_u32 s81, s77, s3
	s_ashr_i32 s17, s14, 6
	s_lshl_b32 s2, s93, 2
	s_lshl_b32 s3, s17, 5
	v_ashrrev_i32_e32 v1, 7, v129
	s_ashr_i32 s11, s14, 7
	s_and_b32 s2, s2, 12
	s_and_b32 s97, s3, 32
	s_lshl_b32 s3, s93, 9
	v_lshlrev_b32_e32 v0, 4, v0
	s_add_i32 s10, s11, s2
	s_and_b32 s87, s3, 0x3800
	v_add3_u32 v0, v1, s2, v0
	s_load_dwordx2 s[2:3], s[0:1], 0x10
	v_ashrrev_i32_e32 v1, 31, v0
	v_and_b32_e32 v18, 31, v129
	s_lshl_b32 s96, s79, 6
	v_or_b32_e32 v126, s97, v18
	s_waitcnt lgkmcnt(0)
	v_lshl_add_u64 v[0:1], v[0:1], 2, s[2:3]
	global_load_dword v0, v[0:1], off
	v_or_b32_e32 v125, s96, v126
	s_add_i32 s86, 0, 0x10000
	v_add_u32_e32 v32, s87, v125
	v_lshl_add_u32 v1, v129, 2, s86
	s_lshl_b32 s84, s10, 7
	v_bfe_u32 v124, v129, 5, 1
	s_ashr_i32 s85, s84, 31
	v_mbcnt_lo_u32_b32 v252, -1, 0
	v_mbcnt_hi_u32_b32 v252, -1, v252
	s_add_i32 s98, s96, s87
	v_and_or_b32 v228, v252, 31, s98
	v_or_b32_e32 v228, s97, v228
	v_mov_b32_e32 v229, 0
	v_lshlrev_b64 v[228:229], 12, v[228:229]
	v_lshl_add_u64 v[228:229], s[76:77], 0, v[228:229]
	v_lshl_add_u64 v[228:229], s[84:85], 1, v[228:229]
	v_lshrrev_b32_e32 v252, 2, v252
	v_and_b32_e32 v252, 8, v252
	v_mov_b32_e32 v253, 0
	v_lshl_add_u64 v[228:229], v[228:229], 0, v[252:253]
	s_mov_b64 s[98:99], 0x25e51000
	v_lshl_add_u64 v[228:229], v[228:229], 0, s[98:99]
	global_load_dwordx2 v[212:213], v[228:229], off
	global_load_dwordx2 v[214:215], v[228:229], off offset:16
	global_load_dwordx2 v[216:217], v[228:229], off offset:32
	global_load_dwordx2 v[218:219], v[228:229], off offset:48
	global_load_dwordx2 v[220:221], v[228:229], off offset:64
	global_load_dwordx2 v[222:223], v[228:229], off offset:80
	global_load_dwordx2 v[224:225], v[228:229], off offset:96
	global_load_dwordx2 v[226:227], v[228:229], off offset:112
	global_load_dwordx2 v[236:237], v[228:229], off offset:128
	global_load_dwordx2 v[238:239], v[228:229], off offset:144
	global_load_dwordx2 v[240:241], v[228:229], off offset:160
	global_load_dwordx2 v[242:243], v[228:229], off offset:176
	global_load_dwordx2 v[244:245], v[228:229], off offset:192
	global_load_dwordx2 v[246:247], v[228:229], off offset:208
	global_load_dwordx2 v[248:249], v[228:229], off offset:224
	global_load_dwordx2 v[250:251], v[228:229], off offset:240
	v_add_u32_e32 v252, s87, v125
	v_lshl_add_u32 v252, v252, 1, v252
	v_lshlrev_b32_e32 v252, 6, v252
	s_lshl_b32 s98, s10, 2
	v_add_u32_e32 v252, s98, v252
	v_mov_b32_e32 v253, 0
	v_lshl_add_u64 v[228:229], s[80:81], 0, v[252:253]
	s_mov_b64 s[98:99], 0x11341000
	v_lshl_add_u64 v[228:229], v[228:229], 0, s[98:99]
	global_load_dword v211, v[228:229], off
	v_lshlrev_b32_e32 v2, 4, v124
	v_mov_b32_e32 v3, v33
	s_mov_b64 s[2:3], 0x21e51000
	s_and_b32 s92, s93, 31
	v_and_b32_e32 v19, 63, v129
	v_lshlrev_b32_e32 v20, 11, v124
	v_lshlrev_b32_e32 v16, 7, v124
	v_sub_u32_e32 v39, v125, v16
	v_max_i32_e32 v17, 31, v39
	v_max_i32_e32 v21, 47, v39
	v_subrev_u32_e32 v17, 31, v17
	v_subrev_u32_e32 v21, 47, v21
	v_min_u32_e32 v17, 0x7f, v17
	v_min_u32_e32 v21, 0x7f, v21
	s_waitcnt vmcnt(0)
	v_mul_f32_e32 v0, 0x3fb8aa3b, v0
	ds_write_b32 v1, v0
	v_lshlrev_b64 v[0:1], 12, v[32:33]
	v_lshl_add_u64 v[0:1], s[80:81], 0, v[0:1]
	v_lshl_add_u64 v[0:1], s[84:85], 1, v[0:1]
	v_lshl_add_u64 v[0:1], v[0:1], 0, v[2:3]
	v_lshl_add_u64 v[2:3], v[0:1], 0, s[2:3]
	s_mov_b32 s2, 0x21e51000
	v_add_co_u32_e32 v0, vcc, s2, v0
	s_lshl_b32 s2, s92, 15
	s_nop 0
	v_addc_co_u32_e32 v1, vcc, 0, v1, vcc
	global_load_dwordx4 v[130:133], v[0:1], off
	global_load_dwordx4 v[134:137], v[2:3], off offset:32
	global_load_dwordx4 v[138:141], v[2:3], off offset:64
	global_load_dwordx4 v[142:145], v[2:3], off offset:96
	global_load_dwordx4 v[146:149], v[2:3], off offset:128
	global_load_dwordx4 v[150:153], v[2:3], off offset:160
	global_load_dwordx4 v[154:157], v[2:3], off offset:192
	global_load_dwordx4 v[158:161], v[2:3], off offset:224
	s_add_u32 s4, s80, s2
	s_addc_u32 s5, s81, 0
	s_lshl_b32 s12, s17, 11
	s_ashr_i32 s13, s12, 31
	s_lshl_b64 s[2:3], s[12:13], 1
	s_add_u32 s2, s4, s2
	s_addc_u32 s3, s5, s3
	v_lshlrev_b32_e32 v0, 4, v19
	v_mov_b32_e32 v1, v33
	v_lshl_add_u64 v[0:1], s[2:3], 0, v[0:1]
	s_mov_b64 s[2:3], 0x4c359000
	v_lshl_add_u64 v[2:3], v[0:1], 0, s[2:3]
	s_lshl_b32 s2, s17, 12
	s_add_i32 s2, s2, 0
	s_mov_b32 m0, s2
	s_mov_b64 s[4:5], 0x4c359400
	global_load_lds_dwordx4 v[2:3], off
	v_lshl_add_u64 v[2:3], v[0:1], 0, s[4:5]
	s_add_i32 m0, s2, 0x400
	s_mov_b64 s[4:5], 0x4c359800
	global_load_lds_dwordx4 v[2:3], off
	v_lshl_add_u64 v[2:3], v[0:1], 0, s[4:5]
	s_add_i32 m0, s2, 0x800
	s_mov_b64 s[4:5], 0x4c359c00
	global_load_lds_dwordx4 v[2:3], off
	v_lshl_add_u64 v[2:3], v[0:1], 0, s[4:5]
	s_add_i32 m0, s2, 0xc00
	s_mov_b64 s[4:5], 0x4c459000
	global_load_lds_dwordx4 v[2:3], off
	v_lshl_add_u64 v[2:3], v[0:1], 0, s[4:5]
	s_add_i32 m0, s2, 0x8000
	s_mov_b64 s[4:5], 0x4c459400
	global_load_lds_dwordx4 v[2:3], off
	v_lshl_add_u64 v[2:3], v[0:1], 0, s[4:5]
	s_add_i32 m0, s2, 0x8400
	s_mov_b64 s[4:5], 0x4c459800
	global_load_lds_dwordx4 v[2:3], off
	v_lshl_add_u64 v[2:3], v[0:1], 0, s[4:5]
	s_add_i32 m0, s2, 0x8800
	s_mov_b64 s[4:5], 0x4c459c00
	global_load_lds_dwordx4 v[2:3], off
	v_lshl_add_u64 v[0:1], v[0:1], 0, s[4:5]
	s_add_i32 m0, s2, 0x8c00
	v_lshlrev_b32_e32 v2, 1, v129
	global_load_lds_dwordx4 v[0:1], off
	v_lshrrev_b32_e32 v1, 1, v129
	v_and_b32_e32 v0, 19, v129
	v_and_b32_e32 v1, 4, v1
	v_and_b32_e32 v2, 8, v2
	v_or3_b32 v0, v0, v1, v2
	v_lshl_add_u32 v127, v0, 4, 0
	s_waitcnt vmcnt(0) lgkmcnt(0)
	s_barrier
	v_add_u32_e32 v40, v127, v20
	ds_read_b128 v[0:3], v40
	ds_read_b128 v[22:25], v40 offset:4096
	s_waitcnt vmcnt(0) lgkmcnt(0)
	v_mfma_f32_32x32x16_bf16 v[0:15], v[0:3], v[130:133], 0
	s_and_b32 s2, s14, 0x3fffff80
	s_lshl_b32 s2, s2, 2
	s_add_i32 s86, s86, s2
	v_lshl_add_u32 v17, v17, 2, s86
	v_lshl_add_u32 v21, v21, 2, s86
	s_cmp_gt_u32 s79, 7
	s_cselect_b64 s[4:5], -1, 0
	v_mfma_f32_32x32x16_bf16 v[0:15], v[22:25], v[134:137], v[0:15]
	ds_read_b128 v[22:25], v40 offset:8192
	s_cmp_lt_u32 s79, 8
	s_waitcnt lgkmcnt(0)
	v_mfma_f32_32x32x16_bf16 v[0:15], v[22:25], v[138:141], v[0:15]
	ds_read_b128 v[22:25], v40 offset:12288
	s_waitcnt lgkmcnt(0)
	v_mfma_f32_32x32x16_bf16 v[0:15], v[22:25], v[142:145], v[0:15]
	ds_read_b128 v[22:25], v40 offset:16384
	s_waitcnt lgkmcnt(0)
	v_mfma_f32_32x32x16_bf16 v[0:15], v[22:25], v[146:149], v[0:15]
	ds_read_b128 v[22:25], v40 offset:20480
	s_waitcnt lgkmcnt(0)
	v_mfma_f32_32x32x16_bf16 v[0:15], v[22:25], v[150:153], v[0:15]
	ds_read_b128 v[22:25], v40 offset:24576
	s_waitcnt lgkmcnt(0)
	v_mfma_f32_32x32x16_bf16 v[0:15], v[22:25], v[154:157], v[0:15]
	ds_read_b128 v[22:25], v40 offset:28672
	s_waitcnt lgkmcnt(0)
	v_mfma_f32_32x32x16_bf16 v[0:15], v[22:25], v[158:161], v[0:15]
	v_max_i32_e32 v22, 63, v39
	v_subrev_u32_e32 v22, 63, v22
	v_min_u32_e32 v22, 0x7f, v22
	v_lshl_add_u32 v24, v22, 2, s86
	v_max_i32_e32 v22, 0x4f, v39
	v_add_u32_e32 v22, 0xffffffb1, v22
	v_min_u32_e32 v22, 0x7f, v22
	v_lshl_add_u32 v25, v22, 2, s86
	v_max_i32_e32 v22, 0x5f, v39
	v_add_u32_e32 v22, 0xffffffa1, v22
	v_min_u32_e32 v22, 0x7f, v22
	v_lshl_add_u32 v26, v22, 2, s86
	v_max_i32_e32 v22, 0x6f, v39
	v_add_u32_e32 v22, 0xffffff91, v22
	v_min_u32_e32 v22, 0x7f, v22
	v_lshl_add_u32 v27, v22, 2, s86
	v_max_i32_e32 v22, 0x7f, v39
	v_add_u32_e32 v22, 0xffffff81, v22
	v_min_u32_e32 v22, 0x7f, v22
	v_lshl_add_u32 v28, v22, 2, s86
	v_max_i32_e32 v22, 0x8f, v39
	v_add_u32_e32 v22, 0xffffff71, v22
	v_min_u32_e32 v22, 0x7f, v22
	v_lshl_add_u32 v29, v22, 2, s86
	v_max_i32_e32 v22, 0x11f, v39
	v_add_u32_e32 v22, 0xfffffee1, v22
	v_min_u32_e32 v22, 0x7f, v22
	v_lshl_add_u32 v30, v22, 2, s86
	v_max_i32_e32 v22, 0x12f, v39
	v_add_u32_e32 v22, 0xfffffed1, v22
	v_min_u32_e32 v22, 0x7f, v22
	v_lshl_add_u32 v31, v22, 2, s86
	v_max_i32_e32 v22, 0x13f, v39
	v_add_u32_e32 v22, 0xfffffec1, v22
	v_min_u32_e32 v22, 0x7f, v22
	v_lshl_add_u32 v34, v22, 2, s86
	v_max_i32_e32 v22, 0x14f, v39
	v_add_u32_e32 v22, 0xfffffeb1, v22
	v_min_u32_e32 v22, 0x7f, v22
	v_lshl_add_u32 v35, v22, 2, s86
	v_max_i32_e32 v22, 0x15f, v39
	v_add_u32_e32 v22, 0xfffffea1, v22
	v_min_u32_e32 v22, 0x7f, v22
	v_lshl_add_u32 v36, v22, 2, s86
	v_max_i32_e32 v22, 0x16f, v39
	v_add_u32_e32 v22, 0xfffffe91, v22
	v_min_u32_e32 v22, 0x7f, v22
	v_lshl_add_u32 v37, v22, 2, s86
	v_max_i32_e32 v22, 0x17f, v39
	v_add_u32_e32 v22, 0xfffffe81, v22
	v_min_u32_e32 v22, 0x7f, v22
	v_lshl_add_u32 v38, v22, 2, s86
	v_max_i32_e32 v22, 0x18f, v39
	v_add_u32_e32 v22, 0xfffffe71, v22
	v_min_u32_e32 v22, 0x7f, v22
	v_lshl_add_u32 v41, v22, 2, s86
	ds_read_b32 v22, v17
	ds_read_b32 v23, v21
	ds_read_b32 v24, v24
	ds_read_b32 v25, v25
	ds_read_b32 v26, v26
	ds_read_b32 v27, v27
	ds_read_b32 v21, v28
	ds_read_b32 v28, v29
	ds_read_b32 v42, v30
	ds_read_b32 v43, v31
	ds_read_b32 v44, v34
	ds_read_b32 v45, v35
	ds_read_b32 v46, v36
	ds_read_b32 v47, v37
	ds_read_b32 v48, v38
	ds_read_b32 v41, v41
	v_or_b32_e32 v29, 47, v16
	s_waitcnt lgkmcnt(14)
	v_or_b32_e32 v30, 31, v16
	v_pk_add_f32 v[0:1], v[0:1], v[22:23]
	v_cmp_ge_u32_e32 vcc, v125, v29
	v_or_b32_e32 v23, 0x4f, v16
	s_waitcnt lgkmcnt(13)
	s_waitcnt lgkmcnt(12)
	v_or_b32_e32 v29, 63, v16
	v_cndmask_b32_e32 v38, v231, v1, vcc
	v_cmp_ge_u32_e32 vcc, v125, v30
	s_waitcnt lgkmcnt(11)
	s_waitcnt lgkmcnt(10)
	s_waitcnt lgkmcnt(9)
	s_waitcnt lgkmcnt(8)
	s_waitcnt lgkmcnt(7)
	v_cndmask_b32_e32 v37, v231, v0, vcc
	v_pk_add_f32 v[0:1], v[2:3], v[24:25]
	v_cmp_ge_u32_e32 vcc, v125, v23
	v_max3_f32 v22, v37, s94, v38
	v_or_b32_e32 v3, 0x6f, v16
	v_cndmask_b32_e32 v36, v231, v1, vcc
	v_cmp_ge_u32_e32 vcc, v125, v29
	s_waitcnt lgkmcnt(6)
	s_waitcnt lgkmcnt(5)
	s_waitcnt lgkmcnt(4)
	s_waitcnt lgkmcnt(3)
	s_waitcnt lgkmcnt(2)
	v_cndmask_b32_e32 v35, v231, v0, vcc
	v_max3_f32 v2, v22, v35, v36
	v_or_b32_e32 v22, 0x5f, v16
	v_pk_add_f32 v[0:1], v[4:5], v[26:27]
	v_cmp_ge_u32_e32 vcc, v125, v3
	v_or_b32_e32 v3, 0x12f, v16
	v_or_b32_e32 v4, 0x11f, v16
	v_cndmask_b32_e32 v34, v231, v1, vcc
	v_cmp_ge_u32_e32 vcc, v125, v22
	v_or_b32_e32 v1, 0x7f, v16
	s_waitcnt lgkmcnt(1)
	s_waitcnt lgkmcnt(0)
	v_mov_b32_e32 v17, v16
	v_cndmask_b32_e32 v31, v231, v0, vcc
	v_max3_f32 v0, v2, v31, v34
	v_add_f32_e32 v2, v6, v21
	v_cmp_ge_u32_e32 vcc, v125, v1
	v_add_u32_e32 v1, 0x8f, v16
	s_nop 0
	v_cndmask_b32_e32 v29, v231, v2, vcc
	v_add_f32_e32 v2, v7, v28
	v_cmp_ge_u32_e32 vcc, v125, v1
	s_nop 1
	v_cndmask_b32_e32 v30, v231, v2, vcc
	v_max3_f32 v2, v0, v29, v30
	v_pk_add_f32 v[0:1], v[8:9], v[42:43]
	v_cmp_ge_u32_e32 vcc, v125, v3
	v_or_b32_e32 v3, 0x14f, v16
	s_nop 0
	v_cndmask_b32_e32 v28, v231, v1, vcc
	v_cmp_ge_u32_e32 vcc, v125, v4
	v_or_b32_e32 v4, 0x13f, v16
	s_nop 0
	v_cndmask_b32_e32 v27, v231, v0, vcc
	v_pk_add_f32 v[0:1], v[10:11], v[44:45]
	v_cmp_ge_u32_e32 vcc, v125, v3
	v_or_b32_e32 v3, 0x16f, v16
	v_max3_f32 v2, v2, v27, v28
	v_cndmask_b32_e32 v26, v231, v1, vcc
	v_cmp_ge_u32_e32 vcc, v125, v4
	v_or_b32_e32 v4, 0x15f, v16
	s_nop 0
	v_cndmask_b32_e32 v25, v231, v0, vcc
	v_pk_add_f32 v[0:1], v[12:13], v[46:47]
	v_cmp_ge_u32_e32 vcc, v125, v3
	v_max3_f32 v2, v2, v25, v26
	s_nop 0
	v_cndmask_b32_e32 v24, v231, v1, vcc
	v_cmp_ge_u32_e32 vcc, v125, v4
	v_or_b32_e32 v1, 0x17f, v16
	s_nop 0
	v_cndmask_b32_e32 v23, v231, v0, vcc
	v_max3_f32 v0, v2, v23, v24
	v_add_f32_e32 v2, v14, v48
	v_cmp_ge_u32_e32 vcc, v125, v1
	v_add_u32_e32 v1, 0x18f, v16
	s_nop 0
	v_cndmask_b32_e32 v21, v231, v2, vcc
	v_add_f32_e32 v2, v15, v41
	v_cmp_ge_u32_e32 vcc, v125, v1
	s_nop 1
	v_cndmask_b32_e32 v22, v231, v2, vcc
	v_max3_f32 v41, v0, v21, v22
	s_cbranch_scc1 .LBB0_1081
	ds_read_b128 v[0:3], v40 offset:512
	ds_read_b128 v[42:45], v40 offset:4608
	v_max_i32_e32 v46, 0x25f, v39
	v_max_i32_e32 v47, 0x26f, v39
	v_max_i32_e32 v48, 0x27f, v39
	v_max_i32_e32 v49, 0x28f, v39
	v_max_i32_e32 v50, 0x31f, v39
	v_max_i32_e32 v51, 0x32f, v39
	v_max_i32_e32 v52, 0x33f, v39
	s_waitcnt lgkmcnt(1)
	v_mfma_f32_32x32x16_bf16 v[0:15], v[0:3], v[130:133], 0
	v_max_i32_e32 v53, 0x34f, v39
	v_max_i32_e32 v54, 0x35f, v39
	v_max_i32_e32 v55, 0x36f, v39
	v_max_i32_e32 v56, 0x37f, v39
	v_add_u32_e32 v46, 0xfffffda1, v46
	v_add_u32_e32 v47, 0xfffffd91, v47
	v_add_u32_e32 v48, 0xfffffd81, v48
	s_waitcnt lgkmcnt(0)
	v_mfma_f32_32x32x16_bf16 v[0:15], v[42:45], v[134:137], v[0:15]
	ds_read_b128 v[42:45], v40 offset:8704
	v_add_u32_e32 v49, 0xfffffd71, v49
	v_add_u32_e32 v50, 0xfffffce1, v50
	v_add_u32_e32 v51, 0xfffffcd1, v51
	v_add_u32_e32 v52, 0xfffffcc1, v52
	v_add_u32_e32 v53, 0xfffffcb1, v53
	v_add_u32_e32 v54, 0xfffffca1, v54
	v_add_u32_e32 v55, 0xfffffc91, v55
	s_waitcnt lgkmcnt(0)
	v_mfma_f32_32x32x16_bf16 v[0:15], v[42:45], v[138:141], v[0:15]
	ds_read_b128 v[42:45], v40 offset:12800
	v_add_u32_e32 v56, 0xfffffc81, v56
	v_max_i32_e32 v57, 0x38f, v39
	v_min_u32_e32 v46, 0x7f, v46
	v_min_u32_e32 v47, 0x7f, v47
	v_min_u32_e32 v48, 0x7f, v48
	v_min_u32_e32 v49, 0x7f, v49
	s_waitcnt lgkmcnt(0)
	v_mfma_f32_32x32x16_bf16 v[0:15], v[42:45], v[142:145], v[0:15]
	ds_read_b128 v[42:45], v40 offset:16896
	v_min_u32_e32 v50, 0x7f, v50
	v_min_u32_e32 v51, 0x7f, v51
	v_min_u32_e32 v52, 0x7f, v52
	v_min_u32_e32 v53, 0x7f, v53
	v_min_u32_e32 v54, 0x7f, v54
	v_min_u32_e32 v55, 0x7f, v55
	s_waitcnt lgkmcnt(0)
	v_mfma_f32_32x32x16_bf16 v[0:15], v[42:45], v[146:149], v[0:15]
	ds_read_b128 v[42:45], v40 offset:20992
	v_min_u32_e32 v56, 0x7f, v56
	v_add_u32_e32 v57, 0xfffffc71, v57
	v_lshl_add_u32 v46, v46, 2, s86
	v_lshl_add_u32 v47, v47, 2, s86
	v_lshl_add_u32 v48, v48, 2, s86
	v_lshl_add_u32 v49, v49, 2, s86
	s_waitcnt lgkmcnt(0)
	v_mfma_f32_32x32x16_bf16 v[0:15], v[42:45], v[150:153], v[0:15]
	ds_read_b128 v[42:45], v40 offset:25088
	v_lshl_add_u32 v50, v50, 2, s86
	v_lshl_add_u32 v51, v51, 2, s86
	v_lshl_add_u32 v52, v52, 2, s86
	v_lshl_add_u32 v53, v53, 2, s86
	v_lshl_add_u32 v54, v54, 2, s86
	v_lshl_add_u32 v55, v55, 2, s86
	s_waitcnt lgkmcnt(0)
	v_mfma_f32_32x32x16_bf16 v[0:15], v[42:45], v[154:157], v[0:15]
	ds_read_b128 v[42:45], v40 offset:29184
	v_lshl_add_u32 v56, v56, 2, s86
	v_min_u32_e32 v57, 0x7f, v57
	v_lshl_add_u32 v57, v57, 2, s86
	s_waitcnt lgkmcnt(0)
	v_mfma_f32_32x32x16_bf16 v[0:15], v[42:45], v[158:161], v[0:15]
	v_max_i32_e32 v42, 0x21f, v39
	v_max_i32_e32 v43, 0x22f, v39
	v_max_i32_e32 v44, 0x23f, v39
	v_max_i32_e32 v45, 0x24f, v39
	v_add_u32_e32 v42, 0xfffffde1, v42
	v_add_u32_e32 v43, 0xfffffdd1, v43
	v_add_u32_e32 v44, 0xfffffdc1, v44
	v_add_u32_e32 v45, 0xfffffdb1, v45
	v_min_u32_e32 v42, 0x7f, v42
	v_min_u32_e32 v43, 0x7f, v43
	v_min_u32_e32 v44, 0x7f, v44
	v_min_u32_e32 v45, 0x7f, v45
	v_lshl_add_u32 v42, v42, 2, s86
	v_lshl_add_u32 v43, v43, 2, s86
	v_lshl_add_u32 v44, v44, 2, s86
	v_lshl_add_u32 v45, v45, 2, s86
	ds_read_b32 v42, v42
	ds_read_b32 v43, v43
	ds_read_b32 v44, v44
	ds_read_b32 v45, v45
	ds_read_b32 v46, v46
	ds_read_b32 v47, v47
	ds_read_b32 v58, v48
	ds_read_b32 v59, v49
	ds_read_b32 v48, v50
	ds_read_b32 v49, v51
	ds_read_b32 v50, v52
	ds_read_b32 v51, v53
	ds_read_b32 v52, v54
	ds_read_b32 v53, v55
	ds_read_b32 v54, v56
	ds_read_b32 v55, v57
	v_or_b32_e32 v56, 0x22f, v17
	s_waitcnt lgkmcnt(14)
	v_or_b32_e32 v57, 0x21f, v16
	v_pk_add_f32 v[0:1], v[0:1], v[42:43]
	v_cmp_ge_u32_e32 vcc, v125, v56
	v_or_b32_e32 v42, 0x24f, v17
	s_waitcnt lgkmcnt(13)
	s_waitcnt lgkmcnt(12)
	v_or_b32_e32 v43, 0x23f, v16
	v_cndmask_b32_e32 v67, v231, v1, vcc
	v_cmp_ge_u32_e32 vcc, v125, v57
	s_waitcnt lgkmcnt(11)
	s_waitcnt lgkmcnt(10)
	s_waitcnt lgkmcnt(9)
	s_waitcnt lgkmcnt(8)
	s_waitcnt lgkmcnt(7)
	v_cndmask_b32_e32 v66, v231, v0, vcc
	v_pk_add_f32 v[0:1], v[2:3], v[44:45]
	v_cmp_ge_u32_e32 vcc, v125, v42
	v_max3_f32 v41, v41, v66, v67
	v_or_b32_e32 v3, 0x26f, v17
	v_cndmask_b32_e32 v69, v231, v1, vcc
	v_cmp_ge_u32_e32 vcc, v125, v43
	s_waitcnt lgkmcnt(6)
	s_waitcnt lgkmcnt(5)
	s_waitcnt lgkmcnt(4)
	s_waitcnt lgkmcnt(3)
	s_waitcnt lgkmcnt(2)
	v_cndmask_b32_e32 v68, v231, v0, vcc
	v_max3_f32 v2, v41, v68, v69
	v_or_b32_e32 v41, 0x25f, v16
	v_pk_add_f32 v[0:1], v[4:5], v[46:47]
	v_cmp_ge_u32_e32 vcc, v125, v3
	v_or_b32_e32 v3, 0x32f, v17
	v_or_b32_e32 v4, 0x31f, v16
	v_cndmask_b32_e32 v71, v231, v1, vcc
	v_cmp_ge_u32_e32 vcc, v125, v41
	v_or_b32_e32 v1, 0x27f, v16
	s_waitcnt lgkmcnt(1)
	s_waitcnt lgkmcnt(0)
	v_cndmask_b32_e32 v70, v231, v0, vcc
	v_max3_f32 v0, v2, v70, v71
	v_add_f32_e32 v2, v6, v58
	v_cmp_ge_u32_e32 vcc, v125, v1
	v_add_u32_e32 v1, 0x28f, v16
	s_nop 0
	v_cndmask_b32_e32 v72, v231, v2, vcc
	v_add_f32_e32 v2, v7, v59
	v_cmp_ge_u32_e32 vcc, v125, v1
	s_nop 1
	v_cndmask_b32_e32 v73, v231, v2, vcc
	v_max3_f32 v2, v0, v72, v73
	v_pk_add_f32 v[0:1], v[8:9], v[48:49]
	v_cmp_ge_u32_e32 vcc, v125, v3
	v_or_b32_e32 v3, 0x34f, v17
	s_nop 0
	v_cndmask_b32_e32 v75, v231, v1, vcc
	v_cmp_ge_u32_e32 vcc, v125, v4
	v_or_b32_e32 v4, 0x33f, v16
	s_nop 0
	v_cndmask_b32_e32 v74, v231, v0, vcc
	v_pk_add_f32 v[0:1], v[10:11], v[50:51]
	v_cmp_ge_u32_e32 vcc, v125, v3
	v_or_b32_e32 v3, 0x36f, v17
	v_max3_f32 v2, v2, v74, v75
	v_cndmask_b32_e32 v77, v231, v1, vcc
	v_cmp_ge_u32_e32 vcc, v125, v4
	v_or_b32_e32 v4, 0x35f, v16
	s_nop 0
	v_cndmask_b32_e32 v76, v231, v0, vcc
	v_pk_add_f32 v[0:1], v[12:13], v[52:53]
	v_cmp_ge_u32_e32 vcc, v125, v3
	v_max3_f32 v2, v2, v76, v77
	s_nop 0
	v_cndmask_b32_e32 v79, v231, v1, vcc
	v_cmp_ge_u32_e32 vcc, v125, v4
	v_or_b32_e32 v1, 0x37f, v16
	s_nop 0
	v_cndmask_b32_e32 v78, v231, v0, vcc
	v_max3_f32 v0, v2, v78, v79
	v_add_f32_e32 v2, v14, v54
	v_cmp_ge_u32_e32 vcc, v125, v1
	v_add_u32_e32 v1, 0x38f, v16
	s_nop 0
	v_cndmask_b32_e32 v80, v231, v2, vcc
	v_add_f32_e32 v2, v15, v55
	v_cmp_ge_u32_e32 vcc, v125, v1
	s_nop 1
	v_cndmask_b32_e32 v81, v231, v2, vcc
	v_max3_f32 v41, v0, v80, v81
	s_cmp_gt_u32 s79, 15
	s_cselect_b64 s[6:7], -1, 0
	s_cmp_lt_u32 s79, 16
	s_cbranch_scc0 .LBB0_1082

.LBB0_1096:
	v_mov_b64_e32 v[66:67], s[80:81]
	v_mad_u64_u32 v[66:67], s[2:3], v32, s50, v[66:67]
	s_ashr_i32 s11, s10, 31
	s_lshl_b32 s2, s92, 19
	v_lshl_add_u64 v[68:69], s[10:11], 2, v[66:67]
	s_add_u32 s2, s80, s2
	v_add_co_u32_e32 v66, vcc, 0x11341000, v68
	v_lshl_or_b32 v32, s17, 10, v162
	s_addc_u32 s3, s81, 0
	v_addc_co_u32_e32 v67, vcc, 0, v69, vcc
	v_lshl_add_u64 v[70:71], v[32:33], 1, s[2:3]
	s_mov_b64 s[2:3], 0x33e51000
	s_add_i32 s62, s12, 0
	v_mov_b32_e32 v66, v211
	s_waitcnt vmcnt(0) lgkmcnt(0)
	s_barrier
	v_lshl_add_u64 v[72:73], v[70:71], 0, s[2:3]
	s_mov_b32 m0, s62
	s_mov_b64 s[2:3], 0x33e51400
	global_load_lds_dwordx4 v[72:73], off
	v_lshl_add_u64 v[72:73], v[70:71], 0, s[2:3]
	s_add_i32 m0, s62, 0x400
	s_mov_b64 s[2:3], 0x34e51000
	global_load_lds_dwordx4 v[72:73], off
	v_lshl_add_u64 v[72:73], v[70:71], 0, s[2:3]
	s_add_i32 m0, s62, 0x8000
	s_mov_b64 s[2:3], 0x34e51400
	global_load_lds_dwordx4 v[72:73], off
	v_lshl_add_u64 v[70:71], v[70:71], 0, s[2:3]
	s_add_i32 m0, s62, 0x8400
	s_andn2_b64 vcc, exec, s[8:9]
	global_load_lds_dwordx4 v[70:71], off
	s_cbranch_vccnz .LBB0_1102
	v_ashrrev_i32_e32 v104, 3, v129
	v_lshlrev_b32_e32 v67, 2, v129
	v_and_b32_e32 v106, 28, v67
	v_mul_lo_u32 v74, v104, s28
	v_add_u32_e32 v75, s44, v74
	v_lshlrev_b32_e32 v102, 2, v106
	v_add_u32_e32 v77, v75, v102
	ds_read2st64_b32 v[70:71], v77 offset1:33
	s_sub_i32 s4, 30, s16
	v_cmp_eq_u32_e32 vcc, 0, v106
	v_cmp_eq_u32_e64 s[2:3], s79, v106
	s_or_b64 s[2:3], vcc, s[2:3]
	s_waitcnt lgkmcnt(0)
	v_add_f32_e32 v70, v70, v71
	ds_read_b32 v71, v77 offset:16896
	ds_read_b32 v78, v77 offset:25344
	v_cmp_eq_u32_e32 vcc, s4, v106
	s_or_b64 vcc, s[2:3], vcc
	v_add_u32_e32 v72, s96, v104
	v_lshl_add_u32 v73, v104, 5, v104
	s_waitcnt lgkmcnt(0)
	v_add_f32_e32 v71, v71, v78
	v_add_f32_e32 v70, v70, v71
	v_lshlrev_b32_e32 v71, 6, v106
	v_cndmask_b32_e32 v78, 0, v232, vcc
	v_add_u32_e32 v76, v106, v73
	v_add_f32_e32 v70, v78, v70
	v_cmp_le_i32_e32 vcc, v71, v72
	v_readlane_b32 s5, v255, 17
	v_or_b32_e32 v107, 2, v106
	v_cndmask_b32_e32 v70, -1.0, v70, vcc
	v_lshl_add_u32 v71, v76, 2, s5
	ds_write_b32 v71, v70
	v_or_b32_e32 v70, 1, v106
	v_lshl_add_u32 v76, v70, 2, v75
	ds_read_b32 v76, v76
	ds_read_b32 v78, v77 offset:8452
	v_cmp_eq_u32_e32 vcc, s79, v70
	v_cmp_eq_u32_e64 s[2:3], s4, v70
	s_or_b64 vcc, vcc, s[2:3]
	v_add_u32_e32 v71, v70, v73
	s_waitcnt lgkmcnt(0)
	v_add_f32_e32 v76, v76, v78
	ds_read_b32 v78, v77 offset:16900
	ds_read_b32 v79, v77 offset:25348
	v_lshl_add_u32 v71, v71, 2, s5
	v_cmp_eq_u32_e64 s[2:3], s4, v107
	v_or_b32_e32 v105, 3, v106
	v_add_u32_e32 v103, s5, v74
	s_waitcnt lgkmcnt(0)
	v_add_f32_e32 v78, v78, v79
	v_add_f32_e32 v76, v76, v78
	v_lshlrev_b32_e32 v78, 6, v70
	v_cndmask_b32_e32 v70, 0, v232, vcc
	v_add_f32_e32 v70, v70, v76
	v_cmp_le_i32_e32 vcc, v78, v72
	v_add_u32_e32 v108, v103, v102
	v_cmp_lt_u32_e64 s[6:7], 4, v106
	v_cndmask_b32_e32 v70, -1.0, v70, vcc
	ds_write_b32 v71, v70
	v_lshl_add_u32 v71, v107, 2, v75
	ds_read_b32 v71, v71
	ds_read_b32 v76, v77 offset:8456
	v_cmp_eq_u32_e32 vcc, s79, v107
	s_or_b64 vcc, vcc, s[2:3]
	v_add_u32_e32 v70, v107, v73
	v_lshl_add_u32 v70, v70, 2, s5
	s_waitcnt lgkmcnt(0)
	v_add_f32_e32 v71, v71, v76
	ds_read_b32 v76, v77 offset:16904
	ds_read_b32 v78, v77 offset:25352
	v_cmp_eq_u32_e64 s[2:3], s4, v105
	v_cmp_lt_u32_e64 s[14:15], 5, v106
	v_cmp_lt_u32_e64 s[8:9], 8, v106
	v_cmp_lt_u32_e64 s[16:17], 9, v106
	s_waitcnt lgkmcnt(0)
	v_add_f32_e32 v76, v76, v78
	v_add_f32_e32 v71, v71, v76
	v_lshlrev_b32_e32 v76, 6, v107
	v_cndmask_b32_e32 v78, 0, v232, vcc
	v_add_f32_e32 v71, v78, v71
	v_cmp_le_i32_e32 vcc, v76, v72
	v_cmp_lt_u32_e64 s[10:11], 12, v106
	v_cmp_lt_u32_e64 s[18:19], 13, v106
	v_cndmask_b32_e32 v71, -1.0, v71, vcc
	ds_write_b32 v70, v71
	v_lshl_add_u32 v71, v105, 2, v75
	v_add_u32_e32 v70, v105, v73
	ds_read_b32 v71, v71
	ds_read_b32 v73, v77 offset:8460
	v_cmp_eq_u32_e32 vcc, s79, v105
	s_or_b64 vcc, vcc, s[2:3]
	v_lshl_add_u32 v70, v70, 2, s5
	v_cmp_lt_u32_e64 s[12:13], 16, v106
	s_waitcnt lgkmcnt(0)
	v_add_f32_e32 v71, v71, v73
	ds_read_b32 v73, v77 offset:16908
	ds_read_b32 v75, v77 offset:25356
	v_cmp_lt_u32_e64 s[20:21], 17, v106
	v_cmp_lt_u32_e64 s[22:23], 20, v106
	v_cmp_lt_u32_e64 s[24:25], 22, v106
	v_cmp_lt_u32_e64 s[52:53], 24, v106
	s_waitcnt lgkmcnt(0)
	v_add_f32_e32 v73, v73, v75
	v_add_f32_e32 v71, v71, v73
	v_lshlrev_b32_e32 v73, 6, v105
	v_cndmask_b32_e32 v75, 0, v232, vcc
	v_add_f32_e32 v71, v75, v71
	v_cmp_le_i32_e32 vcc, v73, v72
	v_cmp_lt_u32_e64 s[56:57], 26, v106
	s_mov_b32 s60, 0
	v_cndmask_b32_e32 v71, -1.0, v71, vcc
	ds_write_b32 v70, v71
	s_waitcnt lgkmcnt(0)
	s_barrier
	ds_read2_b32 v[100:101], v103 offset1:1
	ds_read2_b32 v[98:99], v103 offset0:2 offset1:3
	ds_read2_b32 v[96:97], v103 offset0:4 offset1:5
	ds_read2_b32 v[94:95], v103 offset0:6 offset1:7
	ds_read2_b32 v[92:93], v103 offset0:8 offset1:9
	ds_read2_b32 v[90:91], v103 offset0:10 offset1:11
	ds_read2_b32 v[88:89], v103 offset0:12 offset1:13
	ds_read2_b32 v[86:87], v103 offset0:14 offset1:15
	ds_read2_b32 v[84:85], v103 offset0:16 offset1:17
	ds_read2_b32 v[82:83], v103 offset0:18 offset1:19
	ds_read2_b32 v[80:81], v103 offset0:20 offset1:21
	ds_read2_b32 v[78:79], v103 offset0:22 offset1:23
	ds_read2_b32 v[76:77], v103 offset0:24 offset1:25
	ds_read2_b32 v[74:75], v103 offset0:26 offset1:27
	ds_read2_b32 v[72:73], v103 offset0:28 offset1:29
	ds_read2_b32 v[70:71], v103 offset0:30 offset1:31
	ds_read2_b32 v[102:103], v108 offset1:1
	v_cmp_ne_u32_e32 vcc, 0, v106
	s_waitcnt lgkmcnt(0)
	v_cmp_eq_f32_e64 s[4:5], v100, v102
	v_cmp_gt_f32_e64 s[2:3], v100, v102
	s_and_b64 s[4:5], vcc, s[4:5]
	s_or_b64 s[26:27], s[2:3], s[4:5]
	v_cmp_eq_f32_e64 s[4:5], v101, v102
	v_cmp_gt_f32_e64 s[2:3], v101, v102
	s_and_b64 s[4:5], vcc, s[4:5]
	s_or_b64 s[2:3], s[2:3], s[4:5]
	v_cmp_eq_f32_e64 s[4:5], v98, v102
	v_cndmask_b32_e64 v109, 0, 1, s[2:3]
	v_cmp_gt_f32_e64 s[2:3], v98, v102
	s_and_b64 s[4:5], vcc, s[4:5]
	s_or_b64 s[2:3], s[2:3], s[4:5]
	v_cmp_eq_f32_e64 s[4:5], v99, v102
	v_cndmask_b32_e64 v110, 0, 1, s[2:3]
	v_cmp_gt_f32_e64 s[2:3], v99, v102
	s_and_b64 s[4:5], vcc, s[4:5]
	s_or_b64 s[28:29], s[2:3], s[4:5]
	v_cmp_eq_f32_e64 s[4:5], v96, v102
	v_cmp_gt_f32_e64 s[2:3], v96, v102
	s_and_b64 s[4:5], s[4:5], s[6:7]
	s_or_b64 s[2:3], s[2:3], s[4:5]
	v_cmp_eq_f32_e64 s[4:5], v97, v102
	v_cndmask_b32_e64 v111, 0, 1, s[2:3]
	v_cmp_gt_f32_e64 s[2:3], v97, v102
	s_and_b64 s[4:5], s[4:5], s[14:15]
	s_or_b64 s[30:31], s[2:3], s[4:5]
	v_cmp_eq_f32_e64 s[4:5], v94, v102
	v_cmp_lt_u32_e64 s[6:7], 6, v106
	v_cmp_gt_f32_e64 s[2:3], v94, v102
	s_and_b64 s[4:5], s[4:5], s[6:7]
	s_or_b64 s[2:3], s[2:3], s[4:5]
	v_cmp_eq_f32_e64 s[6:7], v95, v102
	v_cmp_lt_u32_e64 s[4:5], 7, v106
	v_cndmask_b32_e64 v112, 0, 1, s[2:3]
	v_cmp_gt_f32_e64 s[2:3], v95, v102
	s_and_b64 s[6:7], s[6:7], s[4:5]
	s_or_b64 s[34:35], s[2:3], s[6:7]
	v_cmp_eq_f32_e64 s[6:7], v92, v102
	v_cmp_gt_f32_e64 s[2:3], v92, v102
	s_and_b64 s[6:7], s[6:7], s[8:9]
	s_or_b64 s[2:3], s[2:3], s[6:7]
	v_cmp_eq_f32_e64 s[6:7], v93, v102
	v_cndmask_b32_e64 v113, 0, 1, s[2:3]
	v_cmp_gt_f32_e64 s[2:3], v93, v102
	s_and_b64 s[6:7], s[6:7], s[16:17]
	s_or_b64 s[36:37], s[2:3], s[6:7]
	v_cmp_eq_f32_e64 s[6:7], v90, v102
	v_cmp_lt_u32_e64 s[8:9], 10, v106
	v_cmp_gt_f32_e64 s[2:3], v90, v102
	s_and_b64 s[6:7], s[6:7], s[8:9]
	s_or_b64 s[2:3], s[2:3], s[6:7]
	v_cmp_eq_f32_e64 s[8:9], v91, v102
	v_cmp_lt_u32_e64 s[6:7], 11, v106
	v_cndmask_b32_e64 v114, 0, 1, s[2:3]
	v_cmp_gt_f32_e64 s[2:3], v91, v102
	s_and_b64 s[8:9], s[8:9], s[6:7]
	s_or_b64 s[38:39], s[2:3], s[8:9]
	v_cmp_eq_f32_e64 s[8:9], v88, v102
	v_cmp_gt_f32_e64 s[2:3], v88, v102
	s_and_b64 s[8:9], s[8:9], s[10:11]
	s_or_b64 s[2:3], s[2:3], s[8:9]
	v_cmp_eq_f32_e64 s[8:9], v89, v102
	v_cndmask_b32_e64 v115, 0, 1, s[2:3]
	v_cmp_gt_f32_e64 s[2:3], v89, v102
	s_and_b64 s[8:9], s[8:9], s[18:19]
	s_or_b64 s[40:41], s[2:3], s[8:9]
	v_cmp_eq_f32_e64 s[8:9], v86, v102
	v_cmp_lt_u32_e64 s[10:11], 14, v106
	v_cmp_gt_f32_e64 s[2:3], v86, v102
	s_and_b64 s[8:9], s[8:9], s[10:11]
	s_or_b64 s[2:3], s[2:3], s[8:9]
	v_cmp_eq_f32_e64 s[10:11], v87, v102
	v_cmp_lt_u32_e64 s[8:9], 15, v106
	v_cndmask_b32_e64 v116, 0, 1, s[2:3]
	v_cmp_gt_f32_e64 s[2:3], v87, v102
	s_and_b64 s[10:11], s[10:11], s[8:9]
	s_or_b64 s[42:43], s[2:3], s[10:11]
	v_cmp_eq_f32_e64 s[10:11], v84, v102
	v_cmp_gt_f32_e64 s[2:3], v84, v102
	s_and_b64 s[10:11], s[10:11], s[12:13]
	s_or_b64 s[2:3], s[2:3], s[10:11]
	v_cmp_eq_f32_e64 s[10:11], v85, v102
	v_cndmask_b32_e64 v117, 0, 1, s[2:3]
	v_cmp_gt_f32_e64 s[2:3], v85, v102
	s_and_b64 s[10:11], s[10:11], s[20:21]
	s_or_b64 s[44:45], s[2:3], s[10:11]
	v_cmp_eq_f32_e64 s[10:11], v82, v102
	v_cmp_lt_u32_e64 s[12:13], 18, v106
	v_cmp_gt_f32_e64 s[2:3], v82, v102
	s_and_b64 s[10:11], s[10:11], s[12:13]
	s_or_b64 s[2:3], s[2:3], s[10:11]
	v_cmp_eq_f32_e64 s[12:13], v83, v102
	v_cmp_lt_u32_e64 s[10:11], 19, v106
	v_cndmask_b32_e64 v118, 0, 1, s[2:3]
	v_cmp_gt_f32_e64 s[2:3], v83, v102
	s_and_b64 s[12:13], s[12:13], s[10:11]
	s_or_b64 s[46:47], s[2:3], s[12:13]
	v_cmp_eq_f32_e64 s[12:13], v80, v102
	v_cmp_gt_f32_e64 s[2:3], v80, v102
	s_and_b64 s[12:13], s[12:13], s[22:23]
	s_or_b64 s[2:3], s[2:3], s[12:13]
	v_cmp_eq_f32_e64 s[12:13], v81, v102
	v_cmp_lt_u32_e64 s[22:23], 21, v106
	v_cndmask_b32_e64 v119, 0, 1, s[2:3]
	v_cmp_gt_f32_e64 s[2:3], v81, v102
	s_and_b64 s[12:13], s[12:13], s[22:23]
	s_or_b64 s[48:49], s[2:3], s[12:13]
	v_cmp_eq_f32_e64 s[12:13], v78, v102
	v_cmp_gt_f32_e64 s[2:3], v78, v102
	s_and_b64 s[12:13], s[12:13], s[24:25]
	s_or_b64 s[2:3], s[2:3], s[12:13]
	v_cmp_eq_f32_e64 s[24:25], v79, v102
	v_cmp_lt_u32_e64 s[12:13], 23, v106
	v_cndmask_b32_e64 v120, 0, 1, s[2:3]
	v_cmp_gt_f32_e64 s[2:3], v79, v102
	s_and_b64 s[24:25], s[24:25], s[12:13]
	s_or_b64 s[50:51], s[2:3], s[24:25]
	v_cmp_eq_f32_e64 s[24:25], v76, v102
	v_cmp_gt_f32_e64 s[2:3], v76, v102
	s_and_b64 s[24:25], s[24:25], s[52:53]
	s_or_b64 s[2:3], s[2:3], s[24:25]
	v_cmp_eq_f32_e64 s[52:53], v77, v102
	v_cmp_lt_u32_e64 s[24:25], 25, v106
	v_cndmask_b32_e64 v121, 0, 1, s[2:3]
	v_cmp_gt_f32_e64 s[2:3], v77, v102
	s_and_b64 s[52:53], s[52:53], s[24:25]
	v_cmp_eq_f32_e64 s[54:55], v74, v102
	s_or_b64 s[52:53], s[2:3], s[52:53]
	v_cmp_gt_f32_e64 s[2:3], v74, v102
	s_and_b64 s[54:55], s[54:55], s[56:57]
	s_or_b64 s[2:3], s[2:3], s[54:55]
	v_cndmask_b32_e64 v122, 0, 1, s[2:3]
	v_cmp_eq_f32_e64 s[56:57], v75, v102
	v_cmp_eq_u32_e64 s[2:3], 28, v106
	v_cmp_gt_f32_e64 s[54:55], v75, v102
	s_and_b64 s[56:57], s[2:3], s[56:57]
	s_or_b64 s[54:55], s[54:55], s[56:57]
	v_cmp_gt_f32_e64 s[56:57], v72, v102
	v_cmp_gt_f32_e64 s[58:59], v70, v102
	s_nop 0
	v_cndmask_b32_e64 v106, 0, 1, s[56:57]
	v_cmp_gt_f32_e64 s[56:57], v73, v102
	v_cndmask_b32_e64 v123, 0, 1, s[58:59]
	v_cmp_gt_f32_e64 s[58:59], v71, v102
	v_addc_co_u32_e64 v102, s[56:57], 0, v106, s[56:57]
	s_nop 0
	v_addc_co_u32_e64 v102, s[56:57], v102, v123, s[58:59]
	v_addc_co_u32_e64 v102, s[26:27], v102, v109, s[26:27]
	v_addc_co_u32_e64 v102, s[26:27], v102, v110, s[28:29]
	v_addc_co_u32_e64 v102, s[26:27], v102, v111, s[30:31]
	v_addc_co_u32_e64 v102, s[26:27], v102, v112, s[34:35]
	v_addc_co_u32_e64 v102, s[26:27], v102, v113, s[36:37]
	v_addc_co_u32_e64 v102, s[26:27], v102, v114, s[38:39]
	v_addc_co_u32_e64 v102, s[26:27], v102, v115, s[40:41]
	v_addc_co_u32_e64 v102, s[26:27], v102, v116, s[42:43]
	v_addc_co_u32_e64 v102, s[26:27], v102, v117, s[44:45]
	v_addc_co_u32_e64 v102, s[26:27], v102, v118, s[46:47]
	v_addc_co_u32_e64 v102, s[26:27], v102, v119, s[48:49]
	v_addc_co_u32_e64 v102, s[26:27], v102, v120, s[50:51]
	v_addc_co_u32_e64 v102, s[26:27], v102, v121, s[52:53]
	v_addc_co_u32_e64 v102, s[26:27], v102, v122, s[54:55]
	v_cmp_gt_u32_e64 s[26:27], 16, v102
	v_lshlrev_b32_e64 v102, v67, 1
	v_cmp_eq_f32_e64 s[28:29], v101, v103
	v_cndmask_b32_e64 v102, 0, v102, s[26:27]
	v_cmp_ge_f32_e64 s[26:27], v100, v103
	s_and_b64 s[28:29], vcc, s[28:29]
	v_cmp_eq_f32_e64 s[30:31], v99, v103
	v_cndmask_b32_e64 v106, 0, 1, s[26:27]
	v_cmp_gt_f32_e64 s[26:27], v101, v103
	s_or_b64 s[26:27], s[26:27], s[28:29]
	v_cmp_eq_f32_e64 s[28:29], v98, v103
	v_cndmask_b32_e64 v109, 0, 1, s[26:27]
	v_cmp_gt_f32_e64 s[26:27], v98, v103
	s_and_b64 s[28:29], vcc, s[28:29]
	s_or_b64 s[26:27], s[26:27], s[28:29]
	v_cmp_gt_f32_e64 s[28:29], v99, v103
	s_and_b64 s[30:31], vcc, s[30:31]
	s_or_b64 s[28:29], s[28:29], s[30:31]
	v_cmp_eq_f32_e64 s[30:31], v96, v103
	v_cndmask_b32_e64 v110, 0, 1, s[28:29]
	v_cmp_gt_f32_e64 s[28:29], v96, v103
	s_and_b64 s[30:31], vcc, s[30:31]
	v_cmp_eq_f32_e64 s[34:35], v97, v103
	s_or_b64 s[28:29], s[28:29], s[30:31]
	v_cmp_gt_f32_e64 s[30:31], v97, v103
	s_and_b64 s[34:35], s[34:35], s[14:15]
	s_or_b64 s[30:31], s[30:31], s[34:35]
	v_cmp_eq_f32_e64 s[34:35], v94, v103
	v_cndmask_b32_e64 v111, 0, 1, s[30:31]
	v_cmp_gt_f32_e64 s[30:31], v94, v103
	s_and_b64 s[34:35], s[34:35], s[14:15]
	v_cmp_eq_f32_e64 s[36:37], v95, v103
	s_or_b64 s[30:31], s[30:31], s[34:35]
	v_cmp_gt_f32_e64 s[34:35], v95, v103
	s_and_b64 s[36:37], s[36:37], s[4:5]
	s_or_b64 s[34:35], s[34:35], s[36:37]
	v_cmp_eq_f32_e64 s[36:37], v92, v103
	v_cndmask_b32_e64 v112, 0, 1, s[34:35]
	v_cmp_gt_f32_e64 s[34:35], v92, v103
	s_and_b64 s[36:37], s[36:37], s[4:5]
	v_cmp_eq_f32_e64 s[38:39], v93, v103
	s_or_b64 s[34:35], s[34:35], s[36:37]
	v_cmp_gt_f32_e64 s[36:37], v93, v103
	s_and_b64 s[38:39], s[38:39], s[16:17]
	s_or_b64 s[36:37], s[36:37], s[38:39]
	v_cmp_eq_f32_e64 s[38:39], v90, v103
	v_cndmask_b32_e64 v113, 0, 1, s[36:37]
	v_cmp_gt_f32_e64 s[36:37], v90, v103
	s_and_b64 s[38:39], s[38:39], s[16:17]
	v_cmp_eq_f32_e64 s[40:41], v91, v103
	s_or_b64 s[36:37], s[36:37], s[38:39]
	v_cmp_gt_f32_e64 s[38:39], v91, v103
	s_and_b64 s[40:41], s[40:41], s[6:7]
	s_or_b64 s[38:39], s[38:39], s[40:41]
	v_cmp_eq_f32_e64 s[40:41], v88, v103
	v_cndmask_b32_e64 v114, 0, 1, s[38:39]
	v_cmp_gt_f32_e64 s[38:39], v88, v103
	s_and_b64 s[40:41], s[40:41], s[6:7]
	v_cmp_eq_f32_e64 s[42:43], v89, v103
	s_or_b64 s[38:39], s[38:39], s[40:41]
	v_cmp_gt_f32_e64 s[40:41], v89, v103
	s_and_b64 s[42:43], s[42:43], s[18:19]
	s_or_b64 s[40:41], s[40:41], s[42:43]
	v_cmp_eq_f32_e64 s[42:43], v86, v103
	v_cndmask_b32_e64 v115, 0, 1, s[40:41]
	v_cmp_gt_f32_e64 s[40:41], v86, v103
	s_and_b64 s[42:43], s[42:43], s[18:19]
	v_cmp_eq_f32_e64 s[44:45], v87, v103
	s_or_b64 s[40:41], s[40:41], s[42:43]
	v_cmp_gt_f32_e64 s[42:43], v87, v103
	s_and_b64 s[44:45], s[44:45], s[8:9]
	s_or_b64 s[42:43], s[42:43], s[44:45]
	v_cmp_eq_f32_e64 s[44:45], v84, v103
	v_cndmask_b32_e64 v116, 0, 1, s[42:43]
	v_cmp_gt_f32_e64 s[42:43], v84, v103
	s_and_b64 s[44:45], s[44:45], s[8:9]
	v_cmp_eq_f32_e64 s[46:47], v85, v103
	s_or_b64 s[42:43], s[42:43], s[44:45]
	v_cmp_gt_f32_e64 s[44:45], v85, v103
	s_and_b64 s[46:47], s[46:47], s[20:21]
	s_or_b64 s[44:45], s[44:45], s[46:47]
	v_cmp_eq_f32_e64 s[46:47], v82, v103
	v_cndmask_b32_e64 v117, 0, 1, s[44:45]
	v_cmp_gt_f32_e64 s[44:45], v82, v103
	s_and_b64 s[46:47], s[46:47], s[20:21]
	v_cmp_eq_f32_e64 s[48:49], v83, v103
	s_or_b64 s[44:45], s[44:45], s[46:47]
	v_cmp_gt_f32_e64 s[46:47], v83, v103
	s_and_b64 s[48:49], s[48:49], s[10:11]
	s_or_b64 s[46:47], s[46:47], s[48:49]
	v_cmp_eq_f32_e64 s[48:49], v80, v103
	v_cndmask_b32_e64 v118, 0, 1, s[46:47]
	v_cmp_gt_f32_e64 s[46:47], v80, v103
	s_and_b64 s[48:49], s[48:49], s[10:11]
	v_cmp_eq_f32_e64 s[50:51], v81, v103
	s_or_b64 s[46:47], s[46:47], s[48:49]
	v_cmp_gt_f32_e64 s[48:49], v81, v103
	s_and_b64 s[50:51], s[50:51], s[22:23]
	s_or_b64 s[48:49], s[48:49], s[50:51]
	v_cmp_eq_f32_e64 s[50:51], v78, v103
	v_cndmask_b32_e64 v119, 0, 1, s[48:49]
	v_cmp_gt_f32_e64 s[48:49], v78, v103
	s_and_b64 s[50:51], s[50:51], s[22:23]
	v_cmp_eq_f32_e64 s[52:53], v79, v103
	s_or_b64 s[48:49], s[48:49], s[50:51]
	v_cmp_gt_f32_e64 s[50:51], v79, v103
	s_and_b64 s[52:53], s[52:53], s[12:13]
	s_or_b64 s[50:51], s[50:51], s[52:53]
	v_cmp_eq_f32_e64 s[52:53], v76, v103
	v_cndmask_b32_e64 v120, 0, 1, s[50:51]
	v_cmp_gt_f32_e64 s[50:51], v76, v103
	s_and_b64 s[52:53], s[52:53], s[12:13]
	v_cmp_eq_f32_e64 s[54:55], v77, v103
	s_or_b64 s[50:51], s[50:51], s[52:53]
	v_cmp_gt_f32_e64 s[52:53], v77, v103
	s_and_b64 s[54:55], s[54:55], s[24:25]
	s_or_b64 s[52:53], s[52:53], s[54:55]
	v_cmp_eq_f32_e64 s[54:55], v74, v103
	v_cndmask_b32_e64 v121, 0, 1, s[52:53]
	v_cmp_gt_f32_e64 s[52:53], v74, v103
	s_and_b64 s[54:55], s[54:55], s[24:25]
	v_cmp_eq_f32_e64 s[56:57], v75, v103
	s_or_b64 s[52:53], s[52:53], s[54:55]
	v_cmp_gt_f32_e64 s[54:55], v75, v103
	s_and_b64 s[56:57], s[2:3], s[56:57]
	s_or_b64 s[54:55], s[54:55], s[56:57]
	v_cmp_eq_f32_e64 s[56:57], v72, v103
	v_cndmask_b32_e64 v122, 0, 1, s[54:55]
	v_cmp_gt_f32_e64 s[54:55], v72, v103
	s_and_b64 s[56:57], s[2:3], s[56:57]
	s_or_b64 s[54:55], s[54:55], s[56:57]
	v_cmp_gt_f32_e64 s[56:57], v73, v103
	v_cmp_gt_f32_e64 s[58:59], v70, v103
	s_nop 1
	v_cndmask_b32_e64 v123, 0, 1, s[58:59]
	v_cmp_gt_f32_e64 s[58:59], v71, v103
	v_addc_co_u32_e64 v103, s[56:57], 0, v106, s[56:57]
	s_nop 0
	v_addc_co_u32_e64 v103, s[56:57], v103, v123, s[58:59]
	v_addc_co_u32_e64 v103, s[26:27], v103, v109, s[26:27]
	v_addc_co_u32_e64 v103, s[26:27], v103, v110, s[28:29]
	v_addc_co_u32_e64 v103, s[26:27], v103, v111, s[30:31]
	v_addc_co_u32_e64 v103, s[26:27], v103, v112, s[34:35]
	v_addc_co_u32_e64 v103, s[26:27], v103, v113, s[36:37]
	v_addc_co_u32_e64 v103, s[26:27], v103, v114, s[38:39]
	v_addc_co_u32_e64 v103, s[26:27], v103, v115, s[40:41]
	v_addc_co_u32_e64 v103, s[26:27], v103, v116, s[42:43]
	v_addc_co_u32_e64 v103, s[26:27], v103, v117, s[44:45]
	v_addc_co_u32_e64 v103, s[26:27], v103, v118, s[46:47]
	v_addc_co_u32_e64 v103, s[26:27], v103, v119, s[48:49]
	v_addc_co_u32_e64 v103, s[26:27], v103, v120, s[50:51]
	v_addc_co_u32_e64 v103, s[26:27], v103, v121, s[52:53]
	v_addc_co_u32_e64 v103, s[26:27], v103, v122, s[54:55]
	v_cmp_gt_u32_e64 s[26:27], 16, v103
	v_lshlrev_b32_e64 v103, v67, 2
	v_cmp_lt_u32_e64 s[34:35], 5, v107
	v_cndmask_b32_e64 v103, 0, v103, s[26:27]
	v_or_b32_e32 v106, v103, v102
	ds_read2_b32 v[102:103], v108 offset0:2 offset1:3
	v_cmp_lt_u32_e64 s[36:37], 9, v107
	v_cmp_lt_u32_e64 s[38:39], 13, v107
	v_cmp_lt_u32_e64 s[40:41], 17, v107
	v_cmp_lt_u32_e64 s[42:43], 21, v107
	s_waitcnt lgkmcnt(0)
	v_cmp_ge_f32_e64 s[28:29], v101, v102
	v_cmp_ge_f32_e64 s[26:27], v100, v102
	v_cmp_eq_f32_e64 s[30:31], v96, v102
	v_cndmask_b32_e64 v108, 0, 1, s[28:29]
	v_addc_co_u32_e64 v108, s[26:27], 0, v108, s[26:27]
	v_cmp_eq_f32_e64 s[28:29], v98, v102
	v_cmp_gt_f32_e64 s[26:27], v98, v102
	s_and_b64 s[28:29], vcc, s[28:29]
	s_or_b64 s[26:27], s[26:27], s[28:29]
	v_cmp_eq_f32_e64 s[28:29], v99, v102
	v_cndmask_b32_e64 v109, 0, 1, s[26:27]
	v_cmp_gt_f32_e64 s[26:27], v99, v102
	s_and_b64 s[28:29], vcc, s[28:29]
	s_or_b64 s[26:27], s[26:27], s[28:29]
	v_cmp_gt_f32_e64 s[28:29], v96, v102
	s_and_b64 s[30:31], vcc, s[30:31]
	s_or_b64 s[28:29], s[28:29], s[30:31]
	v_cmp_eq_f32_e64 s[30:31], v97, v102
	v_cndmask_b32_e64 v110, 0, 1, s[28:29]
	v_cmp_gt_f32_e64 s[28:29], v97, v102
	s_and_b64 s[30:31], s[30:31], s[34:35]
	v_cmp_eq_f32_e64 s[34:35], v94, v102
	s_or_b64 s[28:29], s[28:29], s[30:31]
	v_cmp_gt_f32_e64 s[30:31], v94, v102
	s_and_b64 s[14:15], s[34:35], s[14:15]
	s_or_b64 s[14:15], s[30:31], s[14:15]
	v_cmp_eq_f32_e64 s[30:31], v95, v102
	v_cndmask_b32_e64 v111, 0, 1, s[14:15]
	v_cmp_gt_f32_e64 s[14:15], v95, v102
	s_and_b64 s[30:31], s[30:31], s[4:5]
	v_cmp_eq_f32_e64 s[34:35], v92, v102
	s_or_b64 s[14:15], s[14:15], s[30:31]
	v_cmp_gt_f32_e64 s[30:31], v92, v102
	s_and_b64 s[34:35], s[34:35], s[4:5]
	s_or_b64 s[30:31], s[30:31], s[34:35]
	v_cmp_eq_f32_e64 s[34:35], v93, v102
	v_cndmask_b32_e64 v112, 0, 1, s[30:31]
	v_cmp_gt_f32_e64 s[30:31], v93, v102
	s_and_b64 s[34:35], s[34:35], s[36:37]
	v_cmp_eq_f32_e64 s[36:37], v90, v102
	s_or_b64 s[30:31], s[30:31], s[34:35]
	v_cmp_gt_f32_e64 s[34:35], v90, v102
	s_and_b64 s[16:17], s[36:37], s[16:17]
	s_or_b64 s[16:17], s[34:35], s[16:17]
	v_cmp_eq_f32_e64 s[34:35], v91, v102
	v_cndmask_b32_e64 v113, 0, 1, s[16:17]
	v_cmp_gt_f32_e64 s[16:17], v91, v102
	s_and_b64 s[34:35], s[34:35], s[6:7]
	v_cmp_eq_f32_e64 s[36:37], v88, v102
	s_or_b64 s[16:17], s[16:17], s[34:35]
	v_cmp_gt_f32_e64 s[34:35], v88, v102
	s_and_b64 s[36:37], s[36:37], s[6:7]
	s_or_b64 s[34:35], s[34:35], s[36:37]
	v_cmp_eq_f32_e64 s[36:37], v89, v102
	v_cndmask_b32_e64 v114, 0, 1, s[34:35]
	v_cmp_gt_f32_e64 s[34:35], v89, v102
	s_and_b64 s[36:37], s[36:37], s[38:39]
	v_cmp_eq_f32_e64 s[38:39], v86, v102
	s_or_b64 s[34:35], s[34:35], s[36:37]
	v_cmp_gt_f32_e64 s[36:37], v86, v102
	s_and_b64 s[18:19], s[38:39], s[18:19]
	s_or_b64 s[18:19], s[36:37], s[18:19]
	v_cmp_eq_f32_e64 s[36:37], v87, v102
	v_cndmask_b32_e64 v115, 0, 1, s[18:19]
	v_cmp_gt_f32_e64 s[18:19], v87, v102
	s_and_b64 s[36:37], s[36:37], s[8:9]
	v_cmp_eq_f32_e64 s[38:39], v84, v102
	s_or_b64 s[18:19], s[18:19], s[36:37]
	v_cmp_gt_f32_e64 s[36:37], v84, v102
	s_and_b64 s[38:39], s[38:39], s[8:9]
	s_or_b64 s[36:37], s[36:37], s[38:39]
	v_cmp_eq_f32_e64 s[38:39], v85, v102
	v_cndmask_b32_e64 v116, 0, 1, s[36:37]
	v_cmp_gt_f32_e64 s[36:37], v85, v102
	s_and_b64 s[38:39], s[38:39], s[40:41]
	v_cmp_eq_f32_e64 s[40:41], v82, v102
	s_or_b64 s[36:37], s[36:37], s[38:39]
	v_cmp_gt_f32_e64 s[38:39], v82, v102
	s_and_b64 s[20:21], s[40:41], s[20:21]
	s_or_b64 s[20:21], s[38:39], s[20:21]
	v_cmp_eq_f32_e64 s[38:39], v83, v102
	v_cndmask_b32_e64 v117, 0, 1, s[20:21]
	v_cmp_gt_f32_e64 s[20:21], v83, v102
	s_and_b64 s[38:39], s[38:39], s[10:11]
	v_cmp_eq_f32_e64 s[40:41], v80, v102
	s_or_b64 s[20:21], s[20:21], s[38:39]
	v_cmp_gt_f32_e64 s[38:39], v80, v102
	s_and_b64 s[40:41], s[40:41], s[10:11]
	s_or_b64 s[38:39], s[38:39], s[40:41]
	v_cmp_eq_f32_e64 s[40:41], v81, v102
	v_cndmask_b32_e64 v118, 0, 1, s[38:39]
	v_cmp_gt_f32_e64 s[38:39], v81, v102
	s_and_b64 s[40:41], s[40:41], s[42:43]
	v_cmp_eq_f32_e64 s[42:43], v78, v102
	s_or_b64 s[38:39], s[38:39], s[40:41]
	v_cmp_gt_f32_e64 s[40:41], v78, v102
	s_and_b64 s[22:23], s[42:43], s[22:23]
	s_or_b64 s[22:23], s[40:41], s[22:23]
	v_cmp_eq_f32_e64 s[40:41], v79, v102
	v_cndmask_b32_e64 v119, 0, 1, s[22:23]
	v_cmp_gt_f32_e64 s[22:23], v79, v102
	s_and_b64 s[40:41], s[40:41], s[12:13]
	v_cmp_eq_f32_e64 s[42:43], v76, v102
	s_or_b64 s[22:23], s[22:23], s[40:41]
	v_cmp_gt_f32_e64 s[40:41], v76, v102
	s_and_b64 s[42:43], s[42:43], s[12:13]
	s_or_b64 s[40:41], s[40:41], s[42:43]
	v_cmp_eq_f32_e64 s[42:43], v77, v102
	v_cmp_lt_u32_e64 s[44:45], 25, v107
	v_cndmask_b32_e64 v120, 0, 1, s[40:41]
	v_cmp_gt_f32_e64 s[40:41], v77, v102
	s_and_b64 s[42:43], s[42:43], s[44:45]
	v_cmp_eq_f32_e64 s[44:45], v74, v102
	s_or_b64 s[40:41], s[40:41], s[42:43]
	v_cmp_gt_f32_e64 s[42:43], v74, v102
	s_and_b64 s[24:25], s[44:45], s[24:25]
	s_or_b64 s[24:25], s[42:43], s[24:25]
	v_cmp_eq_f32_e64 s[42:43], v75, v102
	v_cndmask_b32_e64 v107, 0, 1, s[24:25]
	v_cmp_gt_f32_e64 s[24:25], v75, v102
	s_and_b64 s[42:43], s[2:3], s[42:43]
	v_cmp_eq_f32_e64 s[44:45], v72, v102
	s_or_b64 s[24:25], s[24:25], s[42:43]
	v_cmp_gt_f32_e64 s[42:43], v72, v102
	s_and_b64 s[44:45], s[2:3], s[44:45]
	s_or_b64 s[42:43], s[42:43], s[44:45]
	v_cmp_eq_f32_e64 s[44:45], v73, v102
	v_cndmask_b32_e64 v121, 0, 1, s[42:43]
	v_cmp_gt_f32_e64 s[42:43], v73, v102
	s_and_b64 s[44:45], s[2:3], s[44:45]
	s_or_b64 s[42:43], s[42:43], s[44:45]
	v_cmp_gt_f32_e64 s[44:45], v70, v102
	s_nop 1
	v_cndmask_b32_e64 v122, 0, 1, s[44:45]
	v_cmp_gt_f32_e64 s[44:45], v71, v102
	s_nop 1
	v_addc_co_u32_e64 v102, s[44:45], v108, v122, s[44:45]
	v_addc_co_u32_e64 v102, s[26:27], v102, v109, s[26:27]
	v_addc_co_u32_e64 v102, s[26:27], v102, v110, s[28:29]
	v_addc_co_u32_e64 v102, s[14:15], v102, v111, s[14:15]
	v_addc_co_u32_e64 v102, s[14:15], v102, v112, s[30:31]
	v_addc_co_u32_e64 v102, s[14:15], v102, v113, s[16:17]
	v_addc_co_u32_e64 v102, s[14:15], v102, v114, s[34:35]
	v_addc_co_u32_e64 v102, s[14:15], v102, v115, s[18:19]
	v_addc_co_u32_e64 v102, s[14:15], v102, v116, s[36:37]
	v_addc_co_u32_e64 v102, s[14:15], v102, v117, s[20:21]
	v_addc_co_u32_e64 v102, s[14:15], v102, v118, s[38:39]
	v_addc_co_u32_e64 v102, s[14:15], v102, v119, s[22:23]
	v_addc_co_u32_e64 v102, s[14:15], v102, v120, s[40:41]
	v_addc_co_u32_e64 v102, s[14:15], v102, v107, s[24:25]
	v_addc_co_u32_e64 v102, s[14:15], v102, v121, s[42:43]
	v_cmp_gt_u32_e64 s[14:15], 16, v102
	v_lshlrev_b32_e64 v102, v67, 4
	v_cmp_ge_f32_e64 s[16:17], v101, v103
	v_cndmask_b32_e64 v102, 0, v102, s[14:15]
	v_cmp_ge_f32_e64 s[14:15], v100, v103
	v_cndmask_b32_e64 v100, 0, 1, s[16:17]
	v_cmp_eq_f32_e64 s[16:17], v99, v103
	v_addc_co_u32_e64 v100, s[14:15], 0, v100, s[14:15]
	v_cmp_ge_f32_e64 s[14:15], v98, v103
	s_and_b64 s[16:17], vcc, s[16:17]
	v_cmp_gt_f32_e32 vcc, v96, v103
	v_cndmask_b32_e64 v98, 0, 1, s[14:15]
	v_cmp_gt_f32_e64 s[14:15], v99, v103
	s_or_b64 s[14:15], s[14:15], s[16:17]
	v_cmp_lt_u32_e64 s[16:17], 4, v105
	v_cndmask_b32_e64 v99, 0, 1, s[14:15]
	v_cmp_eq_f32_e64 s[14:15], v96, v103
	s_and_b64 s[14:15], s[14:15], s[16:17]
	v_cmp_eq_f32_e64 s[16:17], v97, v103
	v_cmp_lt_u32_e64 s[18:19], 5, v105
	s_or_b64 vcc, vcc, s[14:15]
	v_cmp_gt_f32_e64 s[14:15], v97, v103
	s_and_b64 s[16:17], s[16:17], s[18:19]
	s_or_b64 s[14:15], s[14:15], s[16:17]
	v_cmp_eq_f32_e64 s[16:17], v94, v103
	v_cmp_lt_u32_e64 s[18:19], 6, v105
	v_cndmask_b32_e64 v96, 0, 1, s[14:15]
	v_cmp_gt_f32_e64 s[14:15], v94, v103
	s_and_b64 s[16:17], s[16:17], s[18:19]
	v_cmp_eq_f32_e64 s[18:19], v95, v103
	s_or_b64 s[14:15], s[14:15], s[16:17]
	v_cmp_gt_f32_e64 s[16:17], v95, v103
	s_and_b64 s[4:5], s[18:19], s[4:5]
	s_or_b64 s[4:5], s[16:17], s[4:5]
	v_cmp_eq_f32_e64 s[16:17], v92, v103
	v_cmp_lt_u32_e64 s[18:19], 8, v105
	v_cndmask_b32_e64 v94, 0, 1, s[4:5]
	v_cmp_gt_f32_e64 s[4:5], v92, v103
	s_and_b64 s[16:17], s[16:17], s[18:19]
	v_cmp_eq_f32_e64 s[18:19], v93, v103
	v_cmp_lt_u32_e64 s[20:21], 9, v105
	s_or_b64 s[4:5], s[4:5], s[16:17]
	v_cmp_gt_f32_e64 s[16:17], v93, v103
	s_and_b64 s[18:19], s[18:19], s[20:21]
	s_or_b64 s[16:17], s[16:17], s[18:19]
	v_cmp_eq_f32_e64 s[18:19], v90, v103
	v_cmp_lt_u32_e64 s[20:21], 10, v105
	v_cndmask_b32_e64 v92, 0, 1, s[16:17]
	v_cmp_gt_f32_e64 s[16:17], v90, v103
	s_and_b64 s[18:19], s[18:19], s[20:21]
	v_cmp_eq_f32_e64 s[20:21], v91, v103
	s_or_b64 s[16:17], s[16:17], s[18:19]
	v_cmp_gt_f32_e64 s[18:19], v91, v103
	s_and_b64 s[6:7], s[20:21], s[6:7]
	s_or_b64 s[6:7], s[18:19], s[6:7]
	v_cmp_eq_f32_e64 s[18:19], v88, v103
	v_cmp_lt_u32_e64 s[20:21], 12, v105
	v_cndmask_b32_e64 v90, 0, 1, s[6:7]
	v_cmp_gt_f32_e64 s[6:7], v88, v103
	s_and_b64 s[18:19], s[18:19], s[20:21]
	v_cmp_eq_f32_e64 s[20:21], v89, v103
	v_cmp_lt_u32_e64 s[22:23], 13, v105
	s_or_b64 s[6:7], s[6:7], s[18:19]
	v_cmp_gt_f32_e64 s[18:19], v89, v103
	s_and_b64 s[20:21], s[20:21], s[22:23]
	s_or_b64 s[18:19], s[18:19], s[20:21]
	v_cmp_eq_f32_e64 s[20:21], v86, v103
	v_cmp_lt_u32_e64 s[22:23], 14, v105
	v_cndmask_b32_e64 v88, 0, 1, s[18:19]
	v_cmp_gt_f32_e64 s[18:19], v86, v103
	s_and_b64 s[20:21], s[20:21], s[22:23]
	v_cmp_eq_f32_e64 s[22:23], v87, v103
	s_or_b64 s[18:19], s[18:19], s[20:21]
	v_cmp_gt_f32_e64 s[20:21], v87, v103
	s_and_b64 s[8:9], s[22:23], s[8:9]
	s_or_b64 s[8:9], s[20:21], s[8:9]
	v_cmp_eq_f32_e64 s[20:21], v84, v103
	v_cmp_lt_u32_e64 s[22:23], 16, v105
	v_cndmask_b32_e64 v86, 0, 1, s[8:9]
	v_cmp_gt_f32_e64 s[8:9], v84, v103
	s_and_b64 s[20:21], s[20:21], s[22:23]
	v_cmp_eq_f32_e64 s[22:23], v85, v103
	v_cmp_lt_u32_e64 s[24:25], 17, v105
	s_or_b64 s[8:9], s[8:9], s[20:21]
	v_cmp_gt_f32_e64 s[20:21], v85, v103
	s_and_b64 s[22:23], s[22:23], s[24:25]
	s_or_b64 s[20:21], s[20:21], s[22:23]
	v_cmp_eq_f32_e64 s[22:23], v82, v103
	v_cmp_lt_u32_e64 s[24:25], 18, v105
	v_cndmask_b32_e64 v84, 0, 1, s[20:21]
	v_cmp_gt_f32_e64 s[20:21], v82, v103
	s_and_b64 s[22:23], s[22:23], s[24:25]
	v_cmp_eq_f32_e64 s[24:25], v83, v103
	s_or_b64 s[20:21], s[20:21], s[22:23]
	v_cmp_gt_f32_e64 s[22:23], v83, v103
	s_and_b64 s[10:11], s[24:25], s[10:11]
	s_or_b64 s[10:11], s[22:23], s[10:11]
	v_cmp_eq_f32_e64 s[22:23], v80, v103
	v_cmp_lt_u32_e64 s[24:25], 20, v105
	v_cndmask_b32_e64 v82, 0, 1, s[10:11]
	v_cmp_gt_f32_e64 s[10:11], v80, v103
	s_and_b64 s[22:23], s[22:23], s[24:25]
	v_cmp_eq_f32_e64 s[24:25], v81, v103
	v_cmp_lt_u32_e64 s[26:27], 21, v105
	s_or_b64 s[10:11], s[10:11], s[22:23]
	v_cmp_gt_f32_e64 s[22:23], v81, v103
	s_and_b64 s[24:25], s[24:25], s[26:27]
	s_or_b64 s[22:23], s[22:23], s[24:25]
	v_cmp_eq_f32_e64 s[24:25], v78, v103
	v_cmp_lt_u32_e64 s[26:27], 22, v105
	v_cndmask_b32_e64 v80, 0, 1, s[22:23]
	v_cmp_gt_f32_e64 s[22:23], v78, v103
	s_and_b64 s[24:25], s[24:25], s[26:27]
	v_cmp_eq_f32_e64 s[26:27], v79, v103
	s_or_b64 s[22:23], s[22:23], s[24:25]
	v_cmp_gt_f32_e64 s[24:25], v79, v103
	s_and_b64 s[12:13], s[26:27], s[12:13]
	s_or_b64 s[12:13], s[24:25], s[12:13]
	v_cmp_eq_f32_e64 s[24:25], v76, v103
	v_cmp_lt_u32_e64 s[26:27], 24, v105
	v_cndmask_b32_e64 v78, 0, 1, s[12:13]
	v_cmp_gt_f32_e64 s[12:13], v76, v103
	s_and_b64 s[24:25], s[24:25], s[26:27]
	v_cmp_eq_f32_e64 s[26:27], v77, v103
	v_cmp_lt_u32_e64 s[28:29], 25, v105
	s_or_b64 s[12:13], s[12:13], s[24:25]
	v_cmp_gt_f32_e64 s[24:25], v77, v103
	s_and_b64 s[26:27], s[26:27], s[28:29]
	s_or_b64 s[24:25], s[24:25], s[26:27]
	v_cmp_eq_f32_e64 s[26:27], v74, v103
	v_cmp_lt_u32_e64 s[28:29], 26, v105
	v_cndmask_b32_e64 v76, 0, 1, s[24:25]
	v_cmp_gt_f32_e64 s[24:25], v74, v103
	s_and_b64 s[26:27], s[26:27], s[28:29]
	v_cmp_eq_f32_e64 s[28:29], v75, v103
	s_or_b64 s[24:25], s[24:25], s[26:27]
	v_cmp_gt_f32_e64 s[26:27], v75, v103
	s_and_b64 s[28:29], s[2:3], s[28:29]
	s_or_b64 s[26:27], s[26:27], s[28:29]
	v_cmp_eq_f32_e64 s[28:29], v72, v103
	v_cmp_lt_u32_e64 s[30:31], 28, v105
	v_cndmask_b32_e64 v74, 0, 1, s[26:27]
	v_cmp_gt_f32_e64 s[26:27], v72, v103
	s_and_b64 s[28:29], s[28:29], s[30:31]
	v_cmp_eq_f32_e64 s[30:31], v73, v103
	v_cmp_lt_u32_e64 s[34:35], 29, v105
	s_or_b64 s[26:27], s[26:27], s[28:29]
	v_cmp_gt_f32_e64 s[28:29], v73, v103
	s_and_b64 s[30:31], s[30:31], s[34:35]
	s_or_b64 s[28:29], s[28:29], s[30:31]
	v_cmp_eq_f32_e64 s[30:31], v70, v103
	v_cndmask_b32_e64 v72, 0, 1, s[28:29]
	v_cmp_gt_f32_e64 s[28:29], v70, v103
	s_and_b64 s[2:3], s[2:3], s[30:31]
	s_or_b64 s[2:3], s[28:29], s[2:3]
	v_cmp_gt_f32_e64 s[28:29], v71, v103
	v_lshlrev_b32_e64 v67, v67, 8
	s_nop 0
	v_addc_co_u32_e64 v70, s[28:29], v100, v98, s[28:29]
	v_addc_co_u32_e32 v70, vcc, v70, v99, vcc
	v_addc_co_u32_e64 v70, vcc, v70, v96, s[14:15]
	v_addc_co_u32_e64 v70, vcc, v70, v94, s[4:5]
	v_addc_co_u32_e64 v70, vcc, v70, v92, s[16:17]
	v_addc_co_u32_e64 v70, vcc, v70, v90, s[6:7]
	v_addc_co_u32_e64 v70, vcc, v70, v88, s[18:19]
	v_addc_co_u32_e64 v70, vcc, v70, v86, s[8:9]
	v_addc_co_u32_e64 v70, vcc, v70, v84, s[20:21]
	v_addc_co_u32_e64 v70, vcc, v70, v82, s[10:11]
	v_addc_co_u32_e64 v70, vcc, v70, v80, s[22:23]
	v_addc_co_u32_e64 v70, vcc, v70, v78, s[12:13]
	v_addc_co_u32_e64 v70, vcc, v70, v76, s[24:25]
	v_addc_co_u32_e64 v70, vcc, v70, v74, s[26:27]
	v_addc_co_u32_e64 v70, vcc, v70, v72, s[2:3]
	v_cmp_gt_u32_e32 vcc, 16, v70
	v_lshl_add_u32 v70, v104, 2, 0
	v_add_u32_e32 v70, 0x1ad00, v70
	v_cndmask_b32_e32 v67, 0, v67, vcc
	v_or3_b32 v67, v106, v102, v67
	s_waitcnt vmcnt(0)
	ds_or_b32 v70, v67
	s_mov_b64 s[2:3], exec
